# pool unit prologue de-serialised: activation loads issued first, the 32 weight-fragment loads moved to just before the window pass
# baseline (speedup 1.0000x reference)
; #define LAS __attribute__((address_space(3)))
; __device__ __forceinline__ int fresh_tid() { int t = threadIdx.x; asm volatile("" : "+v"(t)); return t; }
; __device__ __forceinline__ float bf_lo(unsigned w) { return __uint_as_float(w << 16); }
; __device__ __forceinline__ float bf_hi(unsigned w) { return __uint_as_float(w & 0xffff0000u); }
; __device__ __forceinline__ void pool_unit(int tile, int g, const bf16_t* QKVU, const float* state_pool, const bf16_t* POOLWT, bf16_t* MIX, LAS unsigned char* lds) {
;     const int tid = fresh_tid(), lane = tid & 63, wid = __builtin_amdgcn_readfirstlane(tid >> 6), fr = lane & 15, fq = lane >> 4;
;     LAS float* U = (LAS float*)lds; LAS bf16_t* Dm = (LAS bf16_t*)(lds + 96256);
;     const bool samp = tile >= 512; const int r0 = tile * 128; const int t0 = r0 & 2047;
;     bf16x8 wv[4][8];
; #pragma unroll
;     for (int ks = 0; ks < 4; ++ks)
; #pragma unroll
;         for (int nf = 0; nf < 8; ++nf) wv[ks][nf] = *(const bf16x8*)(POOLWT + (size_t)(g * 128 + 16 * nf + fr) * 128 + 32 * ks + 8 * fq);
;     if (!samp) {
;         u32x4 uw[5];
; #pragma unroll
;         for (int it = 0; it < 5; ++it) { const int idx = tid + 512 * it, row = idx >> 4, ch = idx & 15;
;             const int grow = max(r0 - 15 + min(row, 142), 0);
;             uw[it] = *(const u32x4*)(QKVU + (size_t)grow * 2048 + 1536 + g * 128 + ch * 8); }
;         asm volatile("" : "+v"(uw[0]), "+v"(uw[1]), "+v"(uw[2]), "+v"(uw[3]), "+v"(uw[4]) :: "memory");
; #pragma unroll
;         for (int it = 0; it < 5; ++it) { const int idx = tid + 512 * it, row = idx >> 4, ch = idx & 15;
;             if (idx < 143 * 16) { f32x4 lo = (f32x4){0.f, 0.f, 0.f, 0.f}, hi4 = lo; const u32x4 w = uw[it];
;                 if (t0 - 15 + row >= 0) { lo = (f32x4){bf_lo(w.x), bf_hi(w.x), bf_lo(w.y), bf_hi(w.y)}; hi4 = (f32x4){bf_lo(w.z), bf_hi(w.z), bf_lo(w.w), bf_hi(w.w)}; }
;                 *(LAS f32x4*)(U + row * 128 + ch * 8) = lo; *(LAS f32x4*)(U + row * 128 + ch * 8 + 4) = hi4; } }
.LBB0_591:
	v_mov_b32_e32 v168, v198
	v_bfe_u32 v166, v168, 4, 2
	s_and_b32 s13, s12, 3
	v_and_b32_e32 v167, 15, v168
	s_ashr_i32 s6, s12, 2
	s_lshl_b32 s14, s6, 7
	s_cmpk_gt_i32 s6, 0x1ff
	s_cselect_b64 s[0:1], -1, 0
	s_and_b32 s16, s14, 0x780
	v_readfirstlane_b32 s15, v168
	s_cmpk_lt_i32 s6, 0x200
	s_mov_b64 s[6:7], -1
	s_cbranch_scc0 .LBB0_613
	v_add_u32_e32 v134, 0x200, v168
	v_lshlrev_b32_e32 v130, 3, v168
	v_ashrrev_i32_e32 v174, 4, v168
	v_ashrrev_i32_e32 v173, 4, v134
	s_add_i32 s6, s14, -15
	v_and_b32_e32 v150, 0x78, v130
	v_min_i32_e32 v130, 0x8e, v174
	v_min_i32_e32 v134, 0x8e, v173
	v_add_u32_e32 v130, s6, v130
	v_add_u32_e32 v134, s6, v134
	v_max_i32_e32 v130, 0, v130
	v_mov_b32_e32 v131, v1
	v_max_i32_e32 v134, 0, v134
	v_mov_b32_e32 v135, v1
	v_lshlrev_b64 v[130:131], 12, v[130:131]
	v_lshlrev_b64 v[134:135], 12, v[134:135]
	v_lshl_add_u64 v[130:131], s[54:55], 0, v[130:131]
	s_lshl_b32 s50, s13, 8
	v_lshl_add_u64 v[134:135], s[54:55], 0, v[134:135]
	v_lshl_add_u64 v[130:131], v[130:131], 0, s[50:51]
	v_lshlrev_b32_e32 v132, 1, v150
	v_mov_b32_e32 v133, v1
	v_lshl_add_u64 v[134:135], v[134:135], 0, s[50:51]
	v_lshl_add_u64 v[130:131], v[130:131], 0, v[132:133]
	v_lshl_add_u64 v[134:135], v[134:135], 0, v[132:133]
	global_load_dwordx4 v[146:149], v[130:131], off offset:3072
	global_load_dwordx4 v[142:145], v[134:135], off offset:3072
	v_add_u32_e32 v130, 0x400, v168
	v_add_u32_e32 v134, 0x600, v168
	v_ashrrev_i32_e32 v172, 4, v130
	v_ashrrev_i32_e32 v171, 4, v134
	v_min_i32_e32 v130, 0x8e, v172
	v_min_i32_e32 v134, 0x8e, v171
	v_add_u32_e32 v130, s6, v130
	v_add_u32_e32 v134, s6, v134
	v_max_i32_e32 v130, 0, v130
	v_mov_b32_e32 v131, v1
	v_max_i32_e32 v134, 0, v134
	v_mov_b32_e32 v135, v1
	v_lshlrev_b64 v[130:131], 12, v[130:131]
	v_lshlrev_b64 v[134:135], 12, v[134:135]
	v_lshl_add_u64 v[130:131], s[54:55], 0, v[130:131]
	v_lshl_add_u64 v[134:135], s[54:55], 0, v[134:135]
	v_lshl_add_u64 v[130:131], v[130:131], 0, s[50:51]
	v_lshl_add_u64 v[134:135], v[134:135], 0, s[50:51]
	v_lshl_add_u64 v[130:131], v[130:131], 0, v[132:133]
	v_lshl_add_u64 v[134:135], v[134:135], 0, v[132:133]
	global_load_dwordx4 v[138:141], v[130:131], off offset:3072
	s_nop 0
	global_load_dwordx4 v[134:137], v[134:135], off offset:3072
	v_add_u32_e32 v130, 0x800, v168
	v_ashrrev_i32_e32 v169, 4, v130
	v_min_i32_e32 v130, 0x8e, v169
	v_add_u32_e32 v130, s6, v130
	v_max_i32_e32 v130, 0, v130
	v_mov_b32_e32 v131, v1
	v_lshlrev_b64 v[130:131], 12, v[130:131]
	v_lshl_add_u64 v[130:131], s[54:55], 0, v[130:131]
	v_lshl_add_u64 v[130:131], v[130:131], 0, s[50:51]
	v_lshl_add_u64 v[130:131], v[130:131], 0, v[132:133]
	global_load_dwordx4 v[130:133], v[130:131], off offset:3072
	s_movk_i32 s6, 0x8f0
	s_sub_i32 s10, 14, s16
	v_lshl_add_u32 v170, v150, 2, 0
	v_cmp_gt_i32_e32 vcc, s6, v168
	s_waitcnt vmcnt(0)
	s_and_saveexec_b64 s[6:7], vcc
	s_cbranch_execz .LBB0_596
	v_cmp_lt_i32_e32 vcc, s10, v174
	v_mov_b32_e32 v150, 0
	v_mov_b32_e32 v151, 0
	v_mov_b32_e32 v152, 0
	v_mov_b32_e32 v153, 0
	v_mov_b32_e32 v154, 0
	v_mov_b32_e32 v155, 0
	v_mov_b32_e32 v156, 0
	v_mov_b32_e32 v157, 0
	s_and_saveexec_b64 s[8:9], vcc
	v_lshlrev_b32_e32 v154, 16, v146
	v_and_b32_e32 v155, 0xffff0000, v146
	v_lshlrev_b32_e32 v156, 16, v147
	v_and_b32_e32 v157, 0xffff0000, v147
	v_lshlrev_b32_e32 v150, 16, v148
	v_and_b32_e32 v151, 0xffff0000, v148
	v_lshlrev_b32_e32 v152, 16, v149
	v_and_b32_e32 v153, 0xffff0000, v149
	s_or_b64 exec, exec, s[8:9]
	v_lshl_add_u32 v146, v174, 9, v170
	ds_write_b128 v146, v[154:157]
	ds_write_b128 v146, v[150:153] offset:16

; #define LAS __attribute__((address_space(3)))
; __device__ __forceinline__ void pool_unit(int tile, int g, const bf16_t* QKVU, const float* state_pool, const bf16_t* POOLWT, bf16_t* MIX, LAS unsigned char* lds) {
;     ...
;     bf16x8 wv[4][8];
; #pragma unroll
;     for (int ks = 0; ks < 4; ++ks)
; #pragma unroll
;         for (int nf = 0; nf < 8; ++nf) wv[ks][nf] = *(const bf16x8*)(POOLWT + (size_t)(g * 128 + 16 * nf + fr) * 128 + 32 * ks + 8 * fq);
;     ...
;     __syncthreads();
;     {
;         const int c = tid & 127, rq = tid >> 7, w = 2 << g;
;         const int ubase = samp ? rq * 47 : 0, tl0 = samp ? 0 : 32 * rq, pos0 = samp ? PAST : (t0 + 32 * rq);
;         const LAS float* Uc = U + (ubase + 15 + tl0) * 128 + c;
;         float wsum = 0.f;
;         for (int j = 1; j < w; ++j) wsum += Uc[-j * 128];
.LBB0_622:
	v_readlane_b32 s98, v254, 28
	v_lshlrev_b32_e32 v0, 4, v166
	v_readlane_b32 s99, v254, 29
	s_nop 1
	v_mov_b32_e32 v9, v1
	v_lshl_add_u64 v[2:3], s[98:99], 0, v[0:1]
	s_lshl_b32 s100, s13, 15
	v_lshl_or_b32 v4, v167, 8, s100
	v_or_b32_e32 v8, 0x1000, v4
	v_lshl_add_u64 v[10:11], v[2:3], 0, v[8:9]
	v_or_b32_e32 v12, 0x2000, v4
	v_mov_b32_e32 v13, v1
	v_lshl_add_u64 v[14:15], v[2:3], 0, v[12:13]
	global_load_dwordx4 v[90:93], v[10:11], off
	global_load_dwordx4 v[94:97], v[14:15], off
	v_or_b32_e32 v10, 0x3000, v4
	v_mov_b32_e32 v11, v1
	v_lshl_add_u64 v[14:15], v[2:3], 0, v[10:11]
	v_or_b32_e32 v18, 0x4000, v4
	v_mov_b32_e32 v19, v1
	v_or_b32_e32 v20, 0x5000, v4
	v_mov_b32_e32 v21, v1
	v_mov_b32_e32 v5, v1
	v_lshl_add_u64 v[16:17], v[2:3], 0, v[18:19]
	global_load_dwordx4 v[106:109], v[14:15], off
	global_load_dwordx4 v[110:113], v[16:17], off
	v_lshl_add_u64 v[14:15], v[2:3], 0, v[20:21]
	v_or_b32_e32 v26, 0x6000, v4
	v_mov_b32_e32 v27, v1
	v_or_b32_e32 v28, 0x7000, v4
	v_mov_b32_e32 v29, v1
	v_lshl_add_u64 v[6:7], v[2:3], 0, v[4:5]
	v_lshl_add_u64 v[16:17], v[2:3], 0, v[26:27]
	global_load_dwordx4 v[114:117], v[14:15], off
	global_load_dwordx4 v[118:121], v[16:17], off
	v_lshl_add_u64 v[4:5], v[2:3], 0, v[28:29]
	v_lshl_add_u64 v[14:15], v[2:3], 0, 64
	global_load_dwordx4 v[126:129], v[6:7], off
	global_load_dwordx4 v[34:37], v[6:7], off offset:64
	v_lshl_add_u64 v[16:17], v[14:15], 0, v[8:9]
	global_load_dwordx4 v[122:125], v[4:5], off
	global_load_dwordx4 v[38:41], v[16:17], off
	v_lshl_add_u64 v[4:5], v[14:15], 0, v[12:13]
	v_lshl_add_u64 v[16:17], v[14:15], 0, v[10:11]
	global_load_dwordx4 v[42:45], v[4:5], off
	global_load_dwordx4 v[46:49], v[16:17], off
	v_lshl_add_u64 v[4:5], v[14:15], 0, v[18:19]
	v_lshl_add_u64 v[16:17], v[14:15], 0, v[20:21]
	global_load_dwordx4 v[50:53], v[4:5], off
	global_load_dwordx4 v[54:57], v[16:17], off
	v_lshl_add_u64 v[4:5], v[14:15], 0, v[26:27]
	v_lshl_add_u64 v[14:15], v[14:15], 0, v[28:29]
	global_load_dwordx4 v[58:61], v[4:5], off
	global_load_dwordx4 v[62:65], v[14:15], off
	v_lshl_add_u64 v[4:5], v[2:3], 0, s[18:19]
	v_lshl_add_u64 v[14:15], v[4:5], 0, v[8:9]
	v_lshl_add_u64 v[16:17], v[4:5], 0, v[12:13]
	global_load_dwordx4 v[66:69], v[14:15], off
	global_load_dwordx4 v[70:73], v[16:17], off
	v_lshl_add_u64 v[14:15], v[4:5], 0, v[10:11]
	s_mov_b64 s[100:101], 0xc0
	v_lshl_add_u64 v[16:17], v[4:5], 0, v[18:19]
	global_load_dwordx4 v[74:77], v[14:15], off
	global_load_dwordx4 v[78:81], v[16:17], off
	v_lshl_add_u64 v[14:15], v[4:5], 0, v[20:21]
	v_lshl_add_u64 v[30:31], v[2:3], 0, s[100:101]
	v_lshl_add_u64 v[16:17], v[4:5], 0, v[26:27]
	global_load_dwordx4 v[82:85], v[14:15], off
	global_load_dwordx4 v[86:89], v[16:17], off
	v_lshl_add_u64 v[14:15], v[4:5], 0, v[28:29]
	global_load_dwordx4 v[102:105], v[6:7], off offset:128
	global_load_dwordx4 v[2:5], v[6:7], off offset:192
	v_lshl_add_u64 v[6:7], v[30:31], 0, v[8:9]
	global_load_dwordx4 v[98:101], v[14:15], off
	s_nop 0
	global_load_dwordx4 v[6:9], v[6:7], off
	v_lshl_add_u64 v[12:13], v[30:31], 0, v[12:13]
	v_lshl_add_u64 v[14:15], v[30:31], 0, v[10:11]
	v_lshl_add_u64 v[18:19], v[30:31], 0, v[18:19]
	v_lshl_add_u64 v[22:23], v[30:31], 0, v[20:21]
	v_lshl_add_u64 v[26:27], v[30:31], 0, v[26:27]
	v_lshl_add_u64 v[30:31], v[30:31], 0, v[28:29]
	global_load_dwordx4 v[10:13], v[12:13], off
	s_nop 0
	global_load_dwordx4 v[14:17], v[14:15], off
	s_nop 0
	global_load_dwordx4 v[18:21], v[18:19], off
	s_nop 0
	global_load_dwordx4 v[22:25], v[22:23], off
	s_nop 0
	global_load_dwordx4 v[26:29], v[26:27], off
	s_nop 0
	global_load_dwordx4 v[30:33], v[30:31], off
	v_ashrrev_i32_e32 v131, 7, v168
	v_lshlrev_b32_e32 v130, 5, v131
	v_mad_u64_u32 v[134:135], s[8:9], v131, 47, 15
	v_or_b32_e32 v132, 15, v130
	v_cndmask_b32_e64 v132, v132, v134, s[0:1]
	v_and_b32_e32 v133, 0x7f, v168
	v_lshlrev_b32_e32 v132, 9, v132
	s_lshl_b32 s6, 2, s13
	v_lshl_or_b32 v134, v133, 2, v132
	v_readlane_b32 s8, v252, 34
	s_add_i32 s7, s6, -1
	s_waitcnt lgkmcnt(0)
	v_add_u32_e32 v135, s8, v134
	v_mov_b32_e32 v134, 0
	s_barrier
